# N18 + DK phase tail round dealt one item per CU (same item index mod 64) instead of eight per CU on 32 CUs
# speedup vs baseline: 1.0080x; 1.0080x over previous
; #define LAS __attribute__((address_space(3)))
; __device__ __forceinline__ unsigned pk2(float lo, float hi) { const f32x2_cv v = {lo, hi}; const bf16x2_cv b = __builtin_convertvector(v, bf16x2_cv); return __builtin_bit_cast(unsigned, b); }
; __device__ __forceinline__ void dk_phase(const Frame& F, const bf16* QKrm, const unsigned char* KT, const unsigned char* VT, const float* BG, unsigned char* ITEMS) {
;     ...
;         const unsigned char* ktb = KT + ((size_t)cb * 16 + hk) * 16384;
;         const unsigned char* vtb = VT + ((size_t)cb * 32 + hv) * 16384;
; #pragma unroll
;         for (int mt = 0; mt < 2; ++mt) {
;             bf16x8_t tb[2][2];
; #pragma unroll
;             for (int tt = 0; tt < 2; ++tt)
; #pragma unroll
;                 for (int s = 0; s < 2; ++s) { const LAS unsigned char* p = TW + (32 * mt + r32) * TROW + (32 * tt + 16 * s + 4 * hi) * 2;
;                     const v2u lo = *(const LAS v2u*)p, hi2 = *(const LAS v2u*)(p + 16); tb[tt][s] = as_frag((v4u){lo.x, lo.y, hi2.x, hi2.y}); }
;             bf16x8_t gf[16];
; #pragma unroll
;             for (int k = 0; k < 16; ++k) gf[k] = as_frag(*(const v4u*)(ktb + k * 1024 + lane * 16));
;             asm volatile("s_waitcnt vmcnt(0)" ::: "memory"); __builtin_amdgcn_sched_barrier(0);
; #pragma unroll
;             for (int dt = 0; dt < 4; ++dt) { f32x16_t acc = f32x16_t{};
; #pragma unroll
;                 for (int tt = 0; tt < 2; ++tt)
; #pragma unroll
;                     for (int s = 0; s < 2; ++s) { const bf16x8_t a = gf[(dt * 2 + tt) * 2 + s];
;                         acc = __builtin_amdgcn_mfma_f32_32x32x16_bf16(a, tb[tt][s], acc, 0, 0, 0); }
; #pragma unroll
;                 for (int st = 0; st < 2; ++st) { v4u wv; wv.x = pk2(acc[8 * st + 0], acc[8 * st + 1]); wv.y = pk2(acc[8 * st + 2], acc[8 * st + 3]); wv.z = pk2(acc[8 * st + 4], acc[8 * st + 5]); wv.w = pk2(acc[8 * st + 6], acc[8 * st + 7]);
;                     *(v4u*)(item + ITEM_W + ((mt * 4 + dt) * 2 + st) * 1024 + lane * 16) = wv; } }
.Ldk_st_done:
	s_waitcnt lgkmcnt(0)
	s_ashr_i32 s21, s20, 31
	s_lshl_b64 s[42:43], s[20:21], 18
	s_lshl_b32 s44, s84, 14
	s_mov_b64 s[46:47], s[86:87]
	s_add_u32 s42, s46, s42
	s_addc_u32 s43, s47, s43
	s_add_u32 s42, s42, s44
	s_addc_u32 s43, s43, 0
	v_lshl_add_u64 v[56:57], s[42:43], 0, v[168:169]
	v_add_co_u32_e32 v60, vcc, s3, v56
	global_load_dwordx4 v[4:7], v[56:57], off
	global_load_dwordx4 v[8:11], v[56:57], off offset:1024
	global_load_dwordx4 v[12:15], v[56:57], off offset:2048
	global_load_dwordx4 v[16:19], v[56:57], off offset:3072
	v_addc_co_u32_e32 v61, vcc, 0, v57, vcc
	v_add_co_u32_e32 v58, vcc, s16, v56
	s_lshl_b64 s[20:21], s[20:21], 19
	s_nop 0
	v_addc_co_u32_e32 v59, vcc, 0, v57, vcc
	v_add_co_u32_e32 v62, vcc, s17, v56
	global_load_dwordx4 v[20:23], v[60:61], off offset:1024
	global_load_dwordx4 v[24:27], v[60:61], off offset:2048
	global_load_dwordx4 v[28:31], v[58:59], off
	global_load_dwordx4 v[64:67], v[58:59], off offset:1024
	global_load_dwordx4 v[68:71], v[58:59], off offset:2048
	global_load_dwordx4 v[72:75], v[58:59], off offset:3072
	v_addc_co_u32_e32 v63, vcc, 0, v57, vcc
	global_load_dwordx4 v[32:35], v[60:61], off offset:3072
	global_load_dwordx4 v[76:79], v[62:63], off
	global_load_dwordx4 v[80:83], v[62:63], off offset:1024
	global_load_dwordx4 v[84:87], v[62:63], off offset:2048
	global_load_dwordx4 v[88:91], v[58:59], off offset:-4096
	global_load_dwordx4 v[92:95], v[62:63], off offset:3072
	s_lshl_b32 s42, s83, 14
	s_add_u32 s20, s81, s20
	s_addc_u32 s21, s89, s21
	s_add_u32 s20, s20, s42
	s_addc_u32 s21, s21, 0
	v_add_u32_e32 v2, s53, v164
	v_lshl_add_u64 v[54:55], s[20:21], 0, v[168:169]
	s_movk_i32 s21, 0x88
	v_mad_u32_u24 v112, v186, s21, v2
	ds_read2_b64 v[96:99], v112 offset1:2
	ds_read2_b64 v[100:103], v112 offset0:4 offset1:6
	ds_read2_b64 v[104:107], v112 offset0:8 offset1:10
	ds_read2_b64 v[108:111], v112 offset0:12 offset1:14
	s_waitcnt vmcnt(0)
	v_lshlrev_b32_e32 v36, 5, v185
	v_ashrrev_i32_e32 v37, 31, v36
	v_lshl_add_u64 v[52:53], s[18:19], 0, v[36:37]
	s_waitcnt vmcnt(15) lgkmcnt(3)
	v_mfma_f32_32x32x16_bf16 v[36:51], v[4:7], v[96:99], 0
	s_mov_b32 s20, 0xffff6000
	s_waitcnt vmcnt(14) lgkmcnt(2)
	v_mfma_f32_32x32x16_bf16 v[36:51], v[8:11], v[100:103], v[36:51]
	s_waitcnt vmcnt(13) lgkmcnt(1)
	v_mfma_f32_32x32x16_bf16 v[36:51], v[12:15], v[104:107], v[36:51]
	s_waitcnt vmcnt(12) lgkmcnt(0)
	v_mfma_f32_32x32x16_bf16 v[36:51], v[16:19], v[108:111], v[36:51]
	s_waitcnt vmcnt(1)
	v_mfma_f32_32x32x16_bf16 v[4:19], v[88:91], v[96:99], 0
	s_nop 9
	v_cvt_pk_bf16_f32 v36, v36, v37
	v_cvt_pk_bf16_f32 v37, v38, v39
	v_cvt_pk_bf16_f32 v38, v40, v41
	v_add_co_u32_e32 v40, vcc, s20, v166
	s_mov_b32 s20, 0xffff7000
	s_nop 0
	v_addc_co_u32_e32 v41, vcc, -1, v167, vcc
	v_mfma_f32_32x32x16_bf16 v[4:19], v[20:23], v[100:103], v[4:19]
	v_cvt_pk_bf16_f32 v39, v42, v43
	global_store_dwordx4 v[40:41], v[36:39], off offset:-512
	s_nop 1
	v_cvt_pk_bf16_f32 v36, v44, v45
	v_cvt_pk_bf16_f32 v37, v46, v47
	v_cvt_pk_bf16_f32 v38, v48, v49
	v_mfma_f32_32x32x16_bf16 v[4:19], v[24:27], v[104:107], v[4:19]
	v_cvt_pk_bf16_f32 v39, v50, v51
	v_mfma_f32_32x32x16_bf16 v[4:19], v[32:35], v[108:111], v[4:19]
	v_mfma_f32_32x32x16_bf16 v[20:35], v[28:31], v[96:99], 0
	s_nop 10
	v_cvt_pk_bf16_f32 v4, v4, v5
	v_cvt_pk_bf16_f32 v5, v6, v7
	v_cvt_pk_bf16_f32 v6, v8, v9
	v_cvt_pk_bf16_f32 v7, v10, v11
	v_mfma_f32_32x32x16_bf16 v[20:35], v[64:67], v[100:103], v[20:35]
	v_add_co_u32_e32 v64, vcc, s20, v166
	s_movk_i32 s20, 0x8000
	s_nop 0
	v_addc_co_u32_e32 v65, vcc, -1, v167, vcc
	global_store_dwordx4 v[64:65], v[36:39], off offset:-3584
	global_store_dwordx4 v[64:65], v[4:7], off offset:-2560
	v_mfma_f32_32x32x16_bf16 v[20:35], v[68:71], v[104:107], v[20:35]
	s_nop 0
	v_cvt_pk_bf16_f32 v4, v12, v13
	v_cvt_pk_bf16_f32 v5, v14, v15
	v_cvt_pk_bf16_f32 v6, v16, v17
	v_cvt_pk_bf16_f32 v7, v18, v19
	global_store_dwordx4 v[64:65], v[4:7], off offset:-1536
	v_mfma_f32_32x32x16_bf16 v[36:51], v[76:79], v[96:99], 0
	v_mfma_f32_32x32x16_bf16 v[36:51], v[80:83], v[100:103], v[36:51]
	v_mfma_f32_32x32x16_bf16 v[36:51], v[84:87], v[104:107], v[36:51]
	v_mfma_f32_32x32x16_bf16 v[20:35], v[72:75], v[108:111], v[20:35]
	v_add_co_u32_e32 v72, vcc, s20, v166
	s_nop 1
	v_addc_co_u32_e32 v73, vcc, -1, v167, vcc
	v_add_co_u32_e32 v66, vcc, s3, v54
	s_waitcnt vmcnt(4)
	v_mfma_f32_32x32x16_bf16 v[36:51], v[92:95], v[108:111], v[36:51]
	s_nop 4
	v_cvt_pk_bf16_f32 v4, v20, v21
	v_cvt_pk_bf16_f32 v5, v22, v23
	v_cvt_pk_bf16_f32 v6, v24, v25
	v_cvt_pk_bf16_f32 v7, v26, v27
	global_store_dwordx4 v[64:65], v[4:7], off offset:-512
	v_addc_co_u32_e32 v67, vcc, 0, v55, vcc
	s_nop 0
	v_cvt_pk_bf16_f32 v4, v28, v29
	v_cvt_pk_bf16_f32 v5, v30, v31
	v_cvt_pk_bf16_f32 v6, v32, v33
	v_cvt_pk_bf16_f32 v7, v34, v35
	global_store_dwordx4 v[72:73], v[4:7], off offset:-3584
	v_add_co_u32_e32 v64, vcc, s16, v54
	s_nop 0
	v_cvt_pk_bf16_f32 v4, v36, v37
	v_cvt_pk_bf16_f32 v5, v38, v39
	v_cvt_pk_bf16_f32 v6, v40, v41
	v_cvt_pk_bf16_f32 v7, v42, v43
	global_store_dwordx4 v[72:73], v[4:7], off offset:-2560
	v_addc_co_u32_e32 v65, vcc, 0, v55, vcc
	s_nop 0
	v_cvt_pk_bf16_f32 v4, v44, v45
	v_cvt_pk_bf16_f32 v5, v46, v47
	v_cvt_pk_bf16_f32 v6, v48, v49
	v_cvt_pk_bf16_f32 v7, v50, v51
	global_store_dwordx4 v[72:73], v[4:7], off offset:-1536
	v_add_co_u32_e32 v68, vcc, s17, v54
	global_load_dwordx4 v[4:7], v[54:55], off
	global_load_dwordx4 v[8:11], v[54:55], off offset:1024
	global_load_dwordx4 v[12:15], v[54:55], off offset:2048
	global_load_dwordx4 v[16:19], v[54:55], off offset:3072
	global_load_dwordx4 v[20:23], v[66:67], off offset:1024
	global_load_dwordx4 v[24:27], v[66:67], off offset:2048
	global_load_dwordx4 v[28:31], v[64:65], off
	global_load_dwordx4 v[74:77], v[64:65], off offset:1024
	global_load_dwordx4 v[78:81], v[64:65], off offset:2048
	global_load_dwordx4 v[82:85], v[64:65], off offset:3072
	v_addc_co_u32_e32 v69, vcc, 0, v55, vcc
	global_load_dwordx4 v[32:35], v[66:67], off offset:3072
	global_load_dwordx4 v[86:89], v[68:69], off
	global_load_dwordx4 v[90:93], v[68:69], off offset:1024
	global_load_dwordx4 v[94:97], v[68:69], off offset:2048
	global_load_dwordx4 v[98:101], v[64:65], off offset:-4096
	global_load_dwordx4 v[102:105], v[68:69], off offset:3072
	v_add_u32_e32 v36, 0x2000, v112
	ds_read2_b64 v[106:109], v36 offset0:64 offset1:66
	ds_read2_b64 v[110:113], v36 offset0:68 offset1:70
	ds_read2_b64 v[114:117], v36 offset0:72 offset1:74
	ds_read2_b64 v[118:121], v36 offset0:76 offset1:78
	s_waitcnt vmcnt(0)
; #define LAS __attribute__((address_space(3)))
; __device__ __forceinline__ unsigned pk2(float lo, float hi) { const f32x2_cv v = {lo, hi}; const bf16x2_cv b = __builtin_convertvector(v, bf16x2_cv); return __builtin_bit_cast(unsigned, b); }
; __device__ __forceinline__ void dk_phase(const Frame& F, const bf16* QKrm, const unsigned char* KT, const unsigned char* VT, const float* BG, unsigned char* ITEMS) {
;     ...
;             bf16x8_t ta[2][2];
; #pragma unroll
;             for (int tt = 0; tt < 2; ++tt)
; #pragma unroll
;                 for (int s = 0; s < 2; ++s) { const LAS unsigned char* p = TU + (32 * mt + r32) * TROW + (32 * tt + 16 * s + 4 * hi) * 2;
;                     const v2u lo = *(const LAS v2u*)p, hi2 = *(const LAS v2u*)(p + 16); ta[tt][s] = as_frag((v4u){lo.x, lo.y, hi2.x, hi2.y}); }
; #pragma unroll
;             for (int k = 0; k < 16; ++k) gf[k] = as_frag(*(const v4u*)(vtb + k * 1024 + lane * 16));
;             asm volatile("s_waitcnt vmcnt(0)" ::: "memory"); __builtin_amdgcn_sched_barrier(0);
; #pragma unroll
;             for (int vt = 0; vt < 4; ++vt) { f32x16_t acc = f32x16_t{};
; #pragma unroll
;                 for (int tt = 0; tt < 2; ++tt)
; #pragma unroll
;                     for (int s = 0; s < 2; ++s) { const bf16x8_t b = gf[(vt * 2 + tt) * 2 + s];
;                         acc = __builtin_amdgcn_mfma_f32_32x32x16_bf16(ta[tt][s], b, acc, 0, 0, 0); }
;                 v4u w0, w1; w0.x = pk2(acc[0], acc[1]); w0.y = pk2(acc[2], acc[3]); w0.z = pk2(acc[4], acc[5]); w0.w = pk2(acc[6], acc[7]);
;                 w1.x = pk2(acc[8], acc[9]); w1.y = pk2(acc[10], acc[11]); w1.z = pk2(acc[12], acc[13]); w1.w = pk2(acc[14], acc[15]);
;                 unsigned char* d = item + ITEM_U + (vt * 2 + mt) * 2048 + lane * 32;
;                 *(v4u*)d = w0; *(v4u*)(d + 16) = w1; }
	s_waitcnt vmcnt(15) lgkmcnt(3)
	v_mfma_f32_32x32x16_bf16 v[36:51], v[106:109], v[4:7], 0
	s_movk_i32 s20, 0xd000
	v_mad_u32_u24 v2, v187, s21, v2
	s_waitcnt vmcnt(14) lgkmcnt(2)
	v_mfma_f32_32x32x16_bf16 v[36:51], v[110:113], v[8:11], v[36:51]
	s_waitcnt vmcnt(13) lgkmcnt(1)
	v_mfma_f32_32x32x16_bf16 v[36:51], v[114:117], v[12:15], v[36:51]
	s_waitcnt vmcnt(12) lgkmcnt(0)
	v_mfma_f32_32x32x16_bf16 v[36:51], v[118:121], v[16:19], v[36:51]
	s_waitcnt vmcnt(1)
	v_mfma_f32_32x32x16_bf16 v[4:19], v[106:109], v[98:101], 0
	s_nop 9
	v_cvt_pk_bf16_f32 v36, v36, v37
	v_cvt_pk_bf16_f32 v37, v38, v39
	v_cvt_pk_bf16_f32 v38, v40, v41
	v_cvt_pk_bf16_f32 v40, v44, v45
	v_add_co_u32_e32 v44, vcc, s90, v52
	v_cvt_pk_bf16_f32 v39, v42, v43
	v_mfma_f32_32x32x16_bf16 v[4:19], v[110:113], v[20:23], v[4:19]
	v_cvt_pk_bf16_f32 v41, v46, v47
	v_cvt_pk_bf16_f32 v42, v48, v49
	v_cvt_pk_bf16_f32 v43, v50, v51
	v_addc_co_u32_e32 v45, vcc, -1, v53, vcc
	global_store_dwordx4 v[44:45], v[36:39], off offset:-512
	global_store_dwordx4 v[44:45], v[40:43], off offset:-496
	v_add_co_u32_e32 v70, vcc, s20, v52
	v_mfma_f32_32x32x16_bf16 v[4:19], v[114:117], v[24:27], v[4:19]
	s_nop 0
	v_addc_co_u32_e32 v71, vcc, -1, v53, vcc
	s_movk_i32 s20, 0xe000
	v_mfma_f32_32x32x16_bf16 v[4:19], v[118:121], v[32:35], v[4:19]
	v_mfma_f32_32x32x16_bf16 v[20:35], v[106:109], v[28:31], 0
	s_nop 10
	v_cvt_pk_bf16_f32 v4, v4, v5
	v_cvt_pk_bf16_f32 v5, v6, v7
	v_cvt_pk_bf16_f32 v6, v8, v9
	v_cvt_pk_bf16_f32 v7, v10, v11
	v_cvt_pk_bf16_f32 v8, v12, v13
	v_cvt_pk_bf16_f32 v9, v14, v15
	v_cvt_pk_bf16_f32 v10, v16, v17
	v_mfma_f32_32x32x16_bf16 v[36:51], v[106:109], v[86:89], 0
	v_cvt_pk_bf16_f32 v11, v18, v19
	global_store_dwordx4 v[70:71], v[4:7], off offset:-512
	global_store_dwordx4 v[70:71], v[8:11], off offset:-496
	v_mfma_f32_32x32x16_bf16 v[20:35], v[110:113], v[74:77], v[20:35]
	v_add_co_u32_e32 v74, vcc, s20, v52
	s_movk_i32 s20, 0xf000
	s_nop 0
	v_addc_co_u32_e32 v75, vcc, -1, v53, vcc
	v_add_co_u32_e32 v76, vcc, s20, v52
	v_mfma_f32_32x32x16_bf16 v[36:51], v[110:113], v[90:93], v[36:51]
	s_nop 0
	v_addc_co_u32_e32 v77, vcc, -1, v53, vcc
	v_mfma_f32_32x32x16_bf16 v[20:35], v[114:117], v[78:81], v[20:35]
	v_mfma_f32_32x32x16_bf16 v[36:51], v[114:117], v[94:97], v[36:51]
	v_mfma_f32_32x32x16_bf16 v[20:35], v[118:121], v[82:85], v[20:35]
	s_waitcnt vmcnt(4)
	v_mfma_f32_32x32x16_bf16 v[36:51], v[118:121], v[102:105], v[36:51]
	s_nop 9
	v_cvt_pk_bf16_f32 v4, v20, v21
	v_cvt_pk_bf16_f32 v5, v22, v23
	v_cvt_pk_bf16_f32 v6, v24, v25
	v_cvt_pk_bf16_f32 v7, v26, v27
	v_cvt_pk_bf16_f32 v8, v28, v29
	v_cvt_pk_bf16_f32 v9, v30, v31
	v_cvt_pk_bf16_f32 v10, v32, v33
	v_cvt_pk_bf16_f32 v11, v34, v35
	global_store_dwordx4 v[74:75], v[4:7], off offset:-512
	global_store_dwordx4 v[74:75], v[8:11], off offset:-496
	s_nop 0
	v_cvt_pk_bf16_f32 v4, v36, v37
	v_cvt_pk_bf16_f32 v5, v38, v39
	v_cvt_pk_bf16_f32 v6, v40, v41
	v_cvt_pk_bf16_f32 v7, v42, v43
	v_cvt_pk_bf16_f32 v8, v44, v45
	v_cvt_pk_bf16_f32 v9, v46, v47
	v_cvt_pk_bf16_f32 v10, v48, v49
	v_cvt_pk_bf16_f32 v11, v50, v51
	global_store_dwordx4 v[76:77], v[4:7], off offset:-512
	global_store_dwordx4 v[76:77], v[8:11], off offset:-496
	global_load_dwordx4 v[4:7], v[56:57], off
	s_nop 0
	global_load_dwordx4 v[8:11], v[56:57], off offset:1024
	global_load_dwordx4 v[12:15], v[56:57], off offset:2048
	global_load_dwordx4 v[16:19], v[56:57], off offset:3072
	global_load_dwordx4 v[36:39], v[60:61], off offset:1024
	global_load_dwordx4 v[40:43], v[60:61], off offset:2048
	global_load_dwordx4 v[44:47], v[60:61], off offset:3072
	global_load_dwordx4 v[48:51], v[62:63], off offset:-4096
	global_load_dwordx4 v[78:81], v[58:59], off offset:-4096
	global_load_dwordx4 v[82:85], v[58:59], off offset:1024
	global_load_dwordx4 v[86:89], v[58:59], off offset:2048
	s_nop 0
	global_load_dwordx4 v[56:59], v[58:59], off offset:3072
	s_nop 0
	global_load_dwordx4 v[90:93], v[62:63], off
	global_load_dwordx4 v[94:97], v[62:63], off offset:1024
	global_load_dwordx4 v[98:101], v[62:63], off offset:2048
	s_nop 0
	global_load_dwordx4 v[60:63], v[62:63], off offset:3072
	ds_read2_b64 v[102:105], v2 offset1:2
	ds_read2_b64 v[106:109], v2 offset0:4 offset1:6
	ds_read2_b64 v[110:113], v2 offset0:8 offset1:10
	ds_read2_b64 v[114:117], v2 offset0:12 offset1:14
	s_waitcnt vmcnt(0)
	s_waitcnt vmcnt(15) lgkmcnt(3)
	v_mfma_f32_32x32x16_bf16 v[20:35], v[4:7], v[102:105], 0
	s_movk_i32 s20, 0x9000
	v_add_u32_e32 v2, 0x2000, v2
	s_waitcnt vmcnt(14) lgkmcnt(2)
	v_mfma_f32_32x32x16_bf16 v[20:35], v[8:11], v[106:109], v[20:35]
	s_waitcnt vmcnt(13) lgkmcnt(1)
	v_mfma_f32_32x32x16_bf16 v[20:35], v[12:15], v[110:113], v[20:35]
	s_waitcnt vmcnt(12) lgkmcnt(0)
	v_mfma_f32_32x32x16_bf16 v[20:35], v[16:19], v[114:117], v[20:35]
	s_waitcnt vmcnt(7)
	v_mfma_f32_32x32x16_bf16 v[4:19], v[78:81], v[102:105], 0
	s_nop 9
	v_cvt_pk_bf16_f32 v20, v20, v21
	v_cvt_pk_bf16_f32 v21, v22, v23
	v_cvt_pk_bf16_f32 v22, v24, v25
	v_cvt_pk_bf16_f32 v23, v26, v27
	global_store_dwordx4 v[72:73], v[20:23], off offset:-512
	v_cvt_pk_bf16_f32 v78, v28, v29
	v_cvt_pk_bf16_f32 v79, v30, v31
	v_mfma_f32_32x32x16_bf16 v[4:19], v[36:39], v[106:109], v[4:19]
	v_cvt_pk_bf16_f32 v80, v32, v33
	v_cvt_pk_bf16_f32 v81, v34, v35
	v_mfma_f32_32x32x16_bf16 v[4:19], v[40:43], v[110:113], v[4:19]
	v_mfma_f32_32x32x16_bf16 v[4:19], v[44:47], v[114:117], v[4:19]
	v_mfma_f32_32x32x16_bf16 v[36:51], v[48:51], v[102:105], 0
	s_nop 10
	v_cvt_pk_bf16_f32 v4, v4, v5
	v_cvt_pk_bf16_f32 v5, v6, v7
	v_cvt_pk_bf16_f32 v6, v8, v9
	v_cvt_pk_bf16_f32 v7, v10, v11
	s_waitcnt vmcnt(4)
; #define LAS __attribute__((address_space(3)))
; #define LDS_WAIT() asm volatile("s_waitcnt lgkmcnt(0)" ::: "memory")
; __device__ __forceinline__ unsigned pk2(float lo, float hi) { const f32x2_cv v = {lo, hi}; const bf16x2_cv b = __builtin_convertvector(v, bf16x2_cv); return __builtin_bit_cast(unsigned, b); }
; __device__ __forceinline__ void dk_phase(const Frame& F, const bf16* QKrm, const unsigned char* KT, const unsigned char* VT, const float* BG, unsigned char* ITEMS) {
;     ...
;             bf16x8_t ta[2][2];
; #pragma unroll
;             for (int tt = 0; tt < 2; ++tt)
; #pragma unroll
;                 for (int s = 0; s < 2; ++s) { const LAS unsigned char* p = TU + (32 * mt + r32) * TROW + (32 * tt + 16 * s + 4 * hi) * 2;
;                     const v2u lo = *(const LAS v2u*)p, hi2 = *(const LAS v2u*)(p + 16); ta[tt][s] = as_frag((v4u){lo.x, lo.y, hi2.x, hi2.y}); }
; #pragma unroll
;             for (int k = 0; k < 16; ++k) gf[k] = as_frag(*(const v4u*)(vtb + k * 1024 + lane * 16));
;             asm volatile("s_waitcnt vmcnt(0)" ::: "memory"); __builtin_amdgcn_sched_barrier(0);
; #pragma unroll
;             for (int vt = 0; vt < 4; ++vt) { f32x16_t acc = f32x16_t{};
; #pragma unroll
;                 for (int tt = 0; tt < 2; ++tt)
; #pragma unroll
;                     for (int s = 0; s < 2; ++s) { const bf16x8_t b = gf[(vt * 2 + tt) * 2 + s];
;                         acc = __builtin_amdgcn_mfma_f32_32x32x16_bf16(ta[tt][s], b, acc, 0, 0, 0); }
;                 v4u w0, w1; w0.x = pk2(acc[0], acc[1]); w0.y = pk2(acc[2], acc[3]); w0.z = pk2(acc[4], acc[5]); w0.w = pk2(acc[6], acc[7]);
;                 w1.x = pk2(acc[8], acc[9]); w1.y = pk2(acc[10], acc[11]); w1.z = pk2(acc[12], acc[13]); w1.w = pk2(acc[14], acc[15]);
;                 unsigned char* d = item + ITEM_U + (vt * 2 + mt) * 2048 + lane * 32;
;                 *(v4u*)d = w0; *(v4u*)(d + 16) = w1; }
;         }
;         LDS_WAIT();
;     }
	v_mfma_f32_32x32x16_bf16 v[20:35], v[90:93], v[102:105], 0
	v_mfma_f32_32x32x16_bf16 v[36:51], v[82:85], v[106:109], v[36:51]
	s_waitcnt vmcnt(3)
	v_mfma_f32_32x32x16_bf16 v[20:35], v[94:97], v[106:109], v[20:35]
	v_mfma_f32_32x32x16_bf16 v[36:51], v[86:89], v[110:113], v[36:51]
	s_waitcnt vmcnt(2)
	v_mfma_f32_32x32x16_bf16 v[20:35], v[98:101], v[110:113], v[20:35]
	v_mfma_f32_32x32x16_bf16 v[36:51], v[56:59], v[114:117], v[36:51]
	v_add_co_u32_e32 v56, vcc, s20, v166
	s_nop 1
	v_addc_co_u32_e32 v57, vcc, -1, v167, vcc
	global_store_dwordx4 v[56:57], v[4:7], off offset:-2560
	global_store_dwordx4 v[56:57], v[78:81], off offset:-3584
	s_waitcnt vmcnt(3)
	v_mfma_f32_32x32x16_bf16 v[20:35], v[60:63], v[114:117], v[20:35]
	v_cvt_pk_bf16_f32 v4, v12, v13
	v_cvt_pk_bf16_f32 v5, v14, v15
	v_cvt_pk_bf16_f32 v6, v16, v17
	v_cvt_pk_bf16_f32 v7, v18, v19
	global_store_dwordx4 v[56:57], v[4:7], off offset:-1536
	s_nop 1
	v_cvt_pk_bf16_f32 v4, v36, v37
	v_cvt_pk_bf16_f32 v5, v38, v39
	v_cvt_pk_bf16_f32 v6, v40, v41
	v_cvt_pk_bf16_f32 v7, v42, v43
	global_store_dwordx4 v[56:57], v[4:7], off offset:-512
	s_nop 1
	v_cvt_pk_bf16_f32 v4, v44, v45
	v_cvt_pk_bf16_f32 v5, v46, v47
	v_cvt_pk_bf16_f32 v6, v48, v49
	v_cvt_pk_bf16_f32 v7, v50, v51
	global_store_dwordx4 v[170:171], v[4:7], off offset:-3584
	s_nop 1
	v_cvt_pk_bf16_f32 v4, v20, v21
	v_cvt_pk_bf16_f32 v5, v22, v23
	v_cvt_pk_bf16_f32 v6, v24, v25
	v_cvt_pk_bf16_f32 v7, v26, v27
	global_store_dwordx4 v[170:171], v[4:7], off offset:-2560
	s_nop 1
	v_cvt_pk_bf16_f32 v4, v28, v29
	v_cvt_pk_bf16_f32 v5, v30, v31
	v_cvt_pk_bf16_f32 v6, v32, v33
	v_cvt_pk_bf16_f32 v7, v34, v35
	global_store_dwordx4 v[170:171], v[4:7], off offset:-1536
	global_load_dwordx4 v[4:7], v[54:55], off
	s_nop 0
	global_load_dwordx4 v[8:11], v[54:55], off offset:1024
	global_load_dwordx4 v[12:15], v[54:55], off offset:2048
	global_load_dwordx4 v[16:19], v[54:55], off offset:3072
	global_load_dwordx4 v[36:39], v[66:67], off offset:1024
	global_load_dwordx4 v[40:43], v[66:67], off offset:2048
	global_load_dwordx4 v[44:47], v[66:67], off offset:3072
	global_load_dwordx4 v[48:51], v[68:69], off offset:-4096
	s_nop 0
	global_load_dwordx4 v[54:57], v[64:65], off offset:-4096
	global_load_dwordx4 v[58:61], v[64:65], off offset:1024
	global_load_dwordx4 v[78:81], v[64:65], off offset:2048
	s_nop 0
	global_load_dwordx4 v[62:65], v[64:65], off offset:3072
	s_nop 0
	global_load_dwordx4 v[82:85], v[68:69], off
	global_load_dwordx4 v[86:89], v[68:69], off offset:1024
	global_load_dwordx4 v[90:93], v[68:69], off offset:2048
	s_nop 0
	global_load_dwordx4 v[66:69], v[68:69], off offset:3072
	ds_read2_b64 v[94:97], v2 offset0:64 offset1:66
	ds_read2_b64 v[98:101], v2 offset0:68 offset1:70
	ds_read2_b64 v[102:105], v2 offset0:72 offset1:74
	ds_read2_b64 v[106:109], v2 offset0:76 offset1:78
	s_waitcnt vmcnt(0)
	s_waitcnt vmcnt(15) lgkmcnt(3)
	v_mfma_f32_32x32x16_bf16 v[20:35], v[94:97], v[4:7], 0
	s_add_i32 s52, s52, s64
	s_mul_i32 s20, s50, 0x52000
	s_add_u32 s18, s18, s20
	s_mul_hi_i32 s20, s64, 0xa400
	s_addc_u32 s19, s19, s20
	s_cmpk_lt_i32 s52, 0x4100
	s_waitcnt vmcnt(14) lgkmcnt(2)
	v_mfma_f32_32x32x16_bf16 v[20:35], v[98:101], v[8:11], v[20:35]
	s_waitcnt vmcnt(13) lgkmcnt(1)
	v_mfma_f32_32x32x16_bf16 v[20:35], v[102:105], v[12:15], v[20:35]
	s_waitcnt vmcnt(12) lgkmcnt(0)
	v_mfma_f32_32x32x16_bf16 v[20:35], v[106:109], v[16:19], v[20:35]
	s_waitcnt vmcnt(7)
	v_mfma_f32_32x32x16_bf16 v[4:19], v[94:97], v[54:57], 0
	s_nop 9
	v_cvt_pk_bf16_f32 v20, v20, v21
	v_cvt_pk_bf16_f32 v21, v22, v23
	v_cvt_pk_bf16_f32 v22, v24, v25
	v_cvt_pk_bf16_f32 v23, v26, v27
	v_cvt_pk_bf16_f32 v54, v28, v29
	v_cvt_pk_bf16_f32 v55, v30, v31
	v_cvt_pk_bf16_f32 v56, v32, v33
	v_mfma_f32_32x32x16_bf16 v[4:19], v[98:101], v[36:39], v[4:19]
	v_cvt_pk_bf16_f32 v57, v34, v35
	global_store_dwordx4 v[70:71], v[20:23], off offset:-2560
	global_store_dwordx4 v[70:71], v[54:57], off offset:-2544
	v_mfma_f32_32x32x16_bf16 v[4:19], v[102:105], v[40:43], v[4:19]
	v_mfma_f32_32x32x16_bf16 v[4:19], v[106:109], v[44:47], v[4:19]
	v_mfma_f32_32x32x16_bf16 v[36:51], v[94:97], v[48:51], 0
	s_nop 10
	v_cvt_pk_bf16_f32 v4, v4, v5
	v_cvt_pk_bf16_f32 v5, v6, v7
	v_cvt_pk_bf16_f32 v6, v8, v9
	v_cvt_pk_bf16_f32 v7, v10, v11
	v_cvt_pk_bf16_f32 v8, v12, v13
	v_cvt_pk_bf16_f32 v9, v14, v15
	v_cvt_pk_bf16_f32 v10, v16, v17
	s_waitcnt vmcnt(5)
	v_mfma_f32_32x32x16_bf16 v[20:35], v[94:97], v[82:85], 0
	v_cvt_pk_bf16_f32 v11, v18, v19
	global_store_dwordx4 v[74:75], v[4:7], off offset:-2560
	global_store_dwordx4 v[74:75], v[8:11], off offset:-2544
	v_mfma_f32_32x32x16_bf16 v[36:51], v[98:101], v[58:61], v[36:51]
	s_waitcnt vmcnt(6)
	v_mfma_f32_32x32x16_bf16 v[20:35], v[98:101], v[86:89], v[20:35]
	v_mfma_f32_32x32x16_bf16 v[36:51], v[102:105], v[78:81], v[36:51]
	s_waitcnt vmcnt(5)
	v_mfma_f32_32x32x16_bf16 v[20:35], v[102:105], v[90:93], v[20:35]
	v_mfma_f32_32x32x16_bf16 v[36:51], v[106:109], v[62:65], v[36:51]
	s_waitcnt vmcnt(4)
	v_mfma_f32_32x32x16_bf16 v[20:35], v[106:109], v[66:69], v[20:35]
	s_nop 9
	v_cvt_pk_bf16_f32 v4, v36, v37
	v_cvt_pk_bf16_f32 v5, v38, v39
	v_cvt_pk_bf16_f32 v6, v40, v41
	v_cvt_pk_bf16_f32 v7, v42, v43
	v_cvt_pk_bf16_f32 v8, v44, v45
	v_cvt_pk_bf16_f32 v9, v46, v47
	v_cvt_pk_bf16_f32 v10, v48, v49
	v_cvt_pk_bf16_f32 v11, v50, v51
	global_store_dwordx4 v[76:77], v[4:7], off offset:-2560
	global_store_dwordx4 v[76:77], v[8:11], off offset:-2544
	s_nop 0
	v_cvt_pk_bf16_f32 v4, v20, v21
	v_cvt_pk_bf16_f32 v5, v22, v23
	v_cvt_pk_bf16_f32 v6, v24, v25
	v_cvt_pk_bf16_f32 v7, v26, v27
	v_cvt_pk_bf16_f32 v8, v28, v29
	v_cvt_pk_bf16_f32 v9, v30, v31
	v_cvt_pk_bf16_f32 v10, v32, v33
	v_cvt_pk_bf16_f32 v11, v34, v35
	global_store_dwordx4 v[52:53], v[4:7], off offset:-2560
	global_store_dwordx4 v[52:53], v[8:11], off offset:-2544
	s_waitcnt lgkmcnt(0)
	s_cmpk_lt_i32 s52, 0x4000
	s_cbranch_scc0 .Ldk_tail

; __device__ __forceinline__ void dk_phase(const Frame& F, const bf16* QKrm, const unsigned char* KT, const unsigned char* VT, const float* BG, unsigned char* ITEMS) {
;     ...
;     for (int it = F.gw; it < NCB * 64; it += F.NGW) {
;         int lane_l = F.lane; asm volatile("" : "+v"(lane_l));
;         const int lane = lane_l, r32 = lane & 31, hi = lane >> 5;
;         const int cb = it >> 6, hv = (it >> 1) & 31, dir = it & 1, hk = hv >> 1;
;         unsigned char* item = ITEMS + (size_t)it * ITEM_BYTES;
.Ldk_tail:
	s_cmpk_ge_i32 s52, 0x4800
	s_cbranch_scc1 .LBB0_595
	s_sub_i32 s98, s52, 0x4000
	s_bfe_u32 s99, s98, 0x30006
	s_and_b32 s32, s98, 7
	s_cmp_lg_u32 s99, s32
	s_cbranch_scc1 .LBB0_595
	s_bfe_u32 s99, s98, 0x20009
	s_lshl_b32 s99, s99, 6
	s_and_b32 s32, s98, 63
	s_or_b32 s99, s99, s32
	s_sub_i32 s98, s98, s99
	s_add_i32 s52, s99, 0x4000
	s_mul_i32 s99, s98, 0xa400
	s_sub_u32 s18, s18, s99
	s_subb_u32 s19, s19, 0
	s_branch .LBB0_461
